# attention: staging writes inside PV block + waves 4-7 start each step 512 cycles late (stagger)
# speedup vs baseline: 1.0101x; 1.0058x over previous
.LBB0_308:
	v_sub_f32_e32 v0, v160, v215
	v_exp_f32_e32 v0, v0
	v_sub_f32_e32 v160, v161, v215
	v_exp_f32_e32 v160, v160
	v_sub_f32_e32 v161, v162, v215
	v_exp_f32_e32 v161, v161
	v_sub_f32_e32 v162, v163, v215
	v_exp_f32_e32 v162, v162
	v_sub_f32_e32 v164, v164, v215
	v_add_f32_e32 v163, v207, v0
	v_exp_f32_e32 v164, v164
	v_add_f32_e32 v163, v160, v163
	v_add_f32_e32 v163, v161, v163
	v_sub_f32_e32 v165, v165, v215
	v_add_f32_e32 v163, v162, v163
	v_exp_f32_e32 v165, v165
	v_sub_f32_e32 v166, v166, v215
	v_exp_f32_e32 v166, v166
	v_sub_f32_e32 v167, v167, v215
	v_add_f32_e32 v163, v164, v163
	v_cvt_pk_bf16_f32 v160, v0, v160
	v_cvt_pk_bf16_f32 v161, v161, v162
	v_cvt_pk_bf16_f32 v162, v164, v165
	v_sub_f32_e32 v164, v169, v215
	v_exp_f32_e32 v167, v167
	v_sub_f32_e32 v0, v168, v215
	v_exp_f32_e32 v168, v164
	v_sub_f32_e32 v164, v170, v215
	v_exp_f32_e32 v169, v164
	v_sub_f32_e32 v164, v171, v215
	v_add_f32_e32 v163, v165, v163
	v_exp_f32_e32 v170, v164
	v_sub_f32_e32 v164, v172, v215
	v_add_f32_e32 v163, v166, v163
	v_exp_f32_e32 v171, v164
	v_sub_f32_e32 v164, v173, v215
	v_sub_f32_e32 v14, v14, v215
	v_sub_f32_e32 v15, v15, v215
	v_add_f32_e32 v175, v167, v163
	v_cvt_pk_bf16_f32 v163, v166, v167
	v_exp_f32_e32 v0, v0
	v_exp_f32_e32 v172, v164
	v_exp_f32_e32 v14, v14
	v_exp_f32_e32 v15, v15
	v_cvt_pk_bf16_f32 v164, v0, v168
	v_cvt_pk_bf16_f32 v165, v169, v170
	v_cvt_pk_bf16_f32 v166, v171, v172
	v_cvt_pk_bf16_f32 v167, v14, v15
	s_waitcnt lgkmcnt(3)
	v_mfma_f32_32x32x16_bf16 v[128:143], v[148:151], v[160:163], v[128:143]
	s_waitcnt lgkmcnt(1)
	v_mfma_f32_32x32x16_bf16 v[112:127], v[156:159], v[160:163], v[112:127]
	v_add_u32_e32 v156, 0x5800, v174
	v_mfma_f32_32x32x16_bf16 v[128:143], v[144:147], v[164:167], v[128:143]
	ds_read2_b64 v[144:147], v156 offset0:228 offset1:230
	s_waitcnt lgkmcnt(1)
	v_mfma_f32_32x32x16_bf16 v[112:127], v[152:155], v[164:167], v[112:127]
	v_add_u32_e32 v152, 0x5000, v174
	ds_read2_b64 v[148:151], v152 offset0:192 offset1:194
	ds_read2_b64 v[152:155], v152 offset0:196 offset1:198
	ds_read2_b64 v[156:159], v156 offset0:224 offset1:226
	s_waitcnt lgkmcnt(2)
	v_mfma_f32_32x32x16_bf16 v[96:111], v[148:151], v[160:163], v[96:111]
	s_waitcnt lgkmcnt(0)
	v_mfma_f32_32x32x16_bf16 v[80:95], v[156:159], v[160:163], v[80:95]
	v_subrev_u32_e32 v250, s73, v213
	s_waitcnt vmcnt(2)
	ds_write_b128 v250, v[2:5] offset:35840
	ds_write_b128 v250, v[6:9] offset:44544
	v_add_u32_e32 v156, 0x7000, v174
	v_mfma_f32_32x32x16_bf16 v[96:111], v[152:155], v[164:167], v[96:111]
	v_add_u32_e32 v152, 0x6800, v174
	v_mfma_f32_32x32x16_bf16 v[80:95], v[144:147], v[164:167], v[80:95]
	ds_read2_b64 v[144:147], v156 offset0:36 offset1:38
	ds_read2_b64 v[148:151], v152 offset1:2
	ds_read2_b64 v[152:155], v152 offset0:4 offset1:6
	ds_read2_b64 v[156:159], v156 offset0:32 offset1:34
	s_waitcnt lgkmcnt(2)
	v_mfma_f32_32x32x16_bf16 v[64:79], v[148:151], v[160:163], v[64:79]
	s_waitcnt lgkmcnt(0)
	v_mfma_f32_32x32x16_bf16 v[48:63], v[156:159], v[160:163], v[48:63]
	v_subrev_u32_e32 v250, s73, v214
	v_add_u32_e32 v2, 0xd000, v250
	v_add_u32_e32 v250, 0xf400, v250
	s_waitcnt vmcnt(0)
	ds_write2_b64 v2, v[10:11], v[12:13] offset1:1
	ds_write2_b64 v250, v[176:177], v[178:179] offset1:1
	v_add_u32_e32 v156, 0x8000, v174
	v_mfma_f32_32x32x16_bf16 v[64:79], v[152:155], v[164:167], v[64:79]
	v_add_u32_e32 v152, 0x7800, v174
	v_mfma_f32_32x32x16_bf16 v[48:63], v[144:147], v[164:167], v[48:63]
	ds_read2_b64 v[144:147], v156 offset0:100 offset1:102
	ds_read2_b64 v[148:151], v152 offset0:64 offset1:66
	ds_read2_b64 v[152:155], v152 offset0:68 offset1:70
	ds_read2_b64 v[156:159], v156 offset0:96 offset1:98
	s_waitcnt lgkmcnt(2)
	v_mfma_f32_32x32x16_bf16 v[32:47], v[148:151], v[160:163], v[32:47]
	s_waitcnt lgkmcnt(0)
	v_mfma_f32_32x32x16_bf16 v[16:31], v[156:159], v[160:163], v[16:31]
	v_mfma_f32_32x32x16_bf16 v[32:47], v[152:155], v[164:167], v[32:47]
	v_mfma_f32_32x32x16_bf16 v[16:31], v[144:147], v[164:167], v[16:31]
	v_add_f32_e32 v0, v0, v175
	v_add_f32_e32 v0, v168, v0
	v_add_f32_e32 v0, v169, v0
	v_add_f32_e32 v0, v170, v0
	v_add_f32_e32 v0, v171, v0
	v_add_f32_e32 v0, v172, v0
	v_add_f32_e32 v0, v14, v0
	v_add_f32_e32 v207, v15, v0
	s_add_i32 s77, s77, 1
	v_lshl_add_u64 v[188:189], v[188:189], 0, 64
	s_mov_b64 vcc, 0x80000
	s_cmp_eq_u32 s79, s77
	v_lshl_add_u64 v[190:191], v[190:191], 0, vcc
	s_branch .Lat_step_end

.Lat_step_end:
	s_waitcnt lgkmcnt(0)
	s_barrier
	s_cbranch_scc1 .LBB0_315
.LBB0_310:
	s_and_b64 vcc, exec, s[40:41]
	s_cbranch_vccz .Lat_nostag
	s_sleep 8
